# GEMM K-loops: first fragment reads ordered for counted waits, DMA pieces behind first 8 MFMAs
# baseline (speedup 1.0000x reference)
; #define MFMA16(a, b, c) __builtin_amdgcn_mfma_f32_16x16x32_bf16((a), (b), (c), 0, 0, 0)
; #define RAW_BARRIER() do { asm volatile("s_waitcnt lgkmcnt(0)" ::: "memory"); __builtin_amdgcn_s_barrier(); } while (0)
; template <int AMODE, bool SWAPO = true>
; DI void mainloop_dma16(f32x4 (&acc)[4][2][2][2], const TD& c, const TD& n, bool hasn, bool primed, int& s, int tid) {
;     ...
;     for (int kt = 0; kt < nk; ++kt) {
;         asm volatile("s_waitcnt vmcnt(0)" ::: "memory");
;         RAW_BARRIER();
;         const int ns = s ^ 1, nkt = kt + 1;
;         const bool doload = nkt < nk;
;         const char* sb = smem + s * C::STAGE;
; #pragma unroll
;         for (int k2 = 0; k2 < 2; ++k2) {
;             const int co = ((4 * k2 + q) ^ key) << 4;
;             bf16x8 fw[2][2];
; #pragma unroll
;             for (int ni = 0; ni < 2; ++ni)
; #pragma unroll
;                 for (int rh = 0; rh < 2; ++rh) fw[ni][rh] = *(const bf16x8*)(sb + b_off + (ni * 32 + rh * 16) * 128 + co);
; #pragma unroll
;             for (int mh = 0; mh < 2; ++mh) {
;                 bf16x8 fx[2][2];
; #pragma unroll
;                 for (int m2 = 0; m2 < 2; ++m2)
; #pragma unroll
;                     for (int ch = 0; ch < 2; ++ch) fx[m2][ch] = *(const bf16x8*)(sb + a_off + ((2 * mh + m2) * 32 + ch * 16) * 128 + co);
;                 asm volatile("" ::: "memory");
;                 if (doload) { const int p0 = (2 * k2 + mh) * 2; piece(c, ao, bo, nkt, ns, p0); piece(c, ao, bo, nkt, ns, p0 + 1); }
;                 asm volatile("" ::: "memory");
; #pragma unroll
;                 for (int m2 = 0; m2 < 2; ++m2)
; #pragma unroll
;                     for (int ni = 0; ni < 2; ++ni)
; #pragma unroll
;                         for (int rh = 0; rh < 2; ++rh)
; #pragma unroll
;                             for (int ch = 0; ch < 2; ++ch)
;                                 acc[2 * mh + m2][ni][rh][ch] = SWAPO ? MFMA16(fw[ni][rh], fx[m2][ch], acc[2 * mh + m2][ni][rh][ch]) : MFMA16(fx[m2][ch], fw[ni][rh], acc[2 * mh + m2][ni][rh][ch]);
;             }
.LBB0_202:
	s_cmp_lt_u32 s55, 15
	s_cselect_b64 s[20:21], -1, 0
	s_lshl_b32 s0, s53, 16
	s_add_i32 s1, s0, 16
	v_add3_u32 v165, s1, v197, v195
	v_add3_u32 v163, s1, v196, v195
	s_waitcnt vmcnt(0)
	v_add_u32_e32 v128, v165, v205
	v_add_u32_e32 v167, v163, v205
	s_waitcnt lgkmcnt(0)
	s_barrier
	ds_read_b128 v[152:155], v167
	ds_read_b128 v[140:143], v128 offset:32768
	ds_read_b128 v[136:139], v128 offset:34816
	ds_read_b128 v[132:135], v128 offset:36864
	ds_read_b128 v[128:131], v128 offset:38912
	ds_read_b128 v[156:159], v167 offset:2048
	ds_read_b128 v[144:147], v167 offset:4096
	ds_read_b128 v[148:151], v167 offset:6144
	s_xor_b32 s0, s0, 0x10000
	s_cmp_gt_u32 s55, 14
	v_add_u32_e32 v161, s0, v204
	s_waitcnt lgkmcnt(6)
	v_mfma_f32_16x16x32_bf16 v[124:127], v[140:143], v[152:155], v[124:127]
	s_waitcnt lgkmcnt(5)
	v_mfma_f32_16x16x32_bf16 v[120:123], v[136:139], v[152:155], v[120:123]
	s_waitcnt lgkmcnt(4)
	v_mfma_f32_16x16x32_bf16 v[112:115], v[132:135], v[152:155], v[112:115]
	s_waitcnt lgkmcnt(3)
	v_mfma_f32_16x16x32_bf16 v[104:107], v[128:131], v[152:155], v[104:107]
	s_waitcnt lgkmcnt(2)
	v_mfma_f32_16x16x32_bf16 v[116:119], v[140:143], v[156:159], v[116:119]
	v_mfma_f32_16x16x32_bf16 v[108:111], v[136:139], v[156:159], v[108:111]
	v_mfma_f32_16x16x32_bf16 v[100:103], v[132:135], v[156:159], v[100:103]
	v_mfma_f32_16x16x32_bf16 v[96:99], v[128:131], v[156:159], v[96:99]
	s_cbranch_scc1 .LBB0_204
	v_readfirstlane_b32 s0, v161
	v_add_u32_e32 v169, 0x400, v161
	v_lshl_add_u64 v[208:209], v[178:179], 0, s[40:41]
	s_mov_b32 m0, s0
	v_readfirstlane_b32 s0, v169
	v_lshl_add_u64 v[214:215], v[180:181], 0, s[40:41]
	global_load_lds_dwordx4 v[208:209], off
	s_mov_b32 m0, s0
	s_nop 0
	global_load_lds_dwordx4 v[214:215], off
.LBB0_204:
	s_andn2_b64 vcc, exec, s[20:21]
	s_waitcnt lgkmcnt(1)
	v_mfma_f32_16x16x32_bf16 v[92:95], v[140:143], v[144:147], v[92:95]
	v_mfma_f32_16x16x32_bf16 v[88:91], v[136:139], v[144:147], v[88:91]
	v_mfma_f32_16x16x32_bf16 v[80:83], v[132:135], v[144:147], v[80:83]
	v_mfma_f32_16x16x32_bf16 v[72:75], v[128:131], v[144:147], v[72:75]
	s_waitcnt lgkmcnt(0)
	v_mfma_f32_16x16x32_bf16 v[84:87], v[140:143], v[148:151], v[84:87]
	v_mfma_f32_16x16x32_bf16 v[76:79], v[136:139], v[148:151], v[76:79]
	v_mfma_f32_16x16x32_bf16 v[68:71], v[132:135], v[148:151], v[68:71]
	v_mfma_f32_16x16x32_bf16 v[64:67], v[128:131], v[148:151], v[64:67]
	ds_read_b128 v[152:155], v167 offset:8192
	ds_read_b128 v[156:159], v167 offset:10240
	ds_read_b128 v[144:147], v167 offset:12288
	ds_read_b128 v[148:151], v167 offset:14336
	v_cndmask_b32_e64 v167, 0, 1, s[20:21]
	v_cmp_ne_u32_e64 s[0:1], 1, v167
	s_cbranch_vccnz .LBB0_206
	v_add_u32_e32 v167, 0x800, v161
	v_lshl_add_u64 v[208:209], v[182:183], 0, s[40:41]
	v_readfirstlane_b32 s20, v167
	v_add_u32_e32 v167, 0xc00, v161
	s_mov_b32 m0, s20
	v_readfirstlane_b32 s20, v167
	v_lshl_add_u64 v[214:215], v[184:185], 0, s[40:41]
	global_load_lds_dwordx4 v[208:209], off
	s_mov_b32 m0, s20
	s_nop 0
	global_load_lds_dwordx4 v[214:215], off

; #define MFMA16(a, b, c) __builtin_amdgcn_mfma_f32_16x16x32_bf16((a), (b), (c), 0, 0, 0)
; #define RAW_BARRIER() do { asm volatile("s_waitcnt lgkmcnt(0)" ::: "memory"); __builtin_amdgcn_s_barrier(); } while (0)
; template <int AMODE, bool SWAPO = true>
; DI void mainloop_dma16(f32x4 (&acc)[4][2][2][2], const TD& c, const TD& n, bool hasn, bool primed, int& s, int tid) {
;     ...
;     for (int kt = 0; kt < nk; ++kt) {
;         asm volatile("s_waitcnt vmcnt(0)" ::: "memory");
;         RAW_BARRIER();
;         const int ns = s ^ 1, nkt = kt + 1;
;         const bool doload = nkt < nk;
;         const char* sb = smem + s * C::STAGE;
; #pragma unroll
;         for (int k2 = 0; k2 < 2; ++k2) {
;             const int co = ((4 * k2 + q) ^ key) << 4;
;             bf16x8 fw[2][2];
; #pragma unroll
;             for (int ni = 0; ni < 2; ++ni)
; #pragma unroll
;                 for (int rh = 0; rh < 2; ++rh) fw[ni][rh] = *(const bf16x8*)(sb + b_off + (ni * 32 + rh * 16) * 128 + co);
; #pragma unroll
;             for (int mh = 0; mh < 2; ++mh) {
;                 bf16x8 fx[2][2];
; #pragma unroll
;                 for (int m2 = 0; m2 < 2; ++m2)
; #pragma unroll
;                     for (int ch = 0; ch < 2; ++ch) fx[m2][ch] = *(const bf16x8*)(sb + a_off + ((2 * mh + m2) * 32 + ch * 16) * 128 + co);
;                 asm volatile("" ::: "memory");
;                 if (doload) { const int p0 = (2 * k2 + mh) * 2; piece(c, ao, bo, nkt, ns, p0); piece(c, ao, bo, nkt, ns, p0 + 1); }
;                 asm volatile("" ::: "memory");
; #pragma unroll
;                 for (int m2 = 0; m2 < 2; ++m2)
; #pragma unroll
;                     for (int ni = 0; ni < 2; ++ni)
; #pragma unroll
;                         for (int rh = 0; rh < 2; ++rh)
; #pragma unroll
;                             for (int ch = 0; ch < 2; ++ch)
;                                 acc[2 * mh + m2][ni][rh][ch] = SWAPO ? MFMA16(fw[ni][rh], fx[m2][ch], acc[2 * mh + m2][ni][rh][ch]) : MFMA16(fx[m2][ch], fw[ni][rh], acc[2 * mh + m2][ni][rh][ch]);
;             }
.LBB0_336:
	s_cmp_lt_u32 s40, 15
	s_cselect_b64 s[20:21], -1, 0
	s_lshl_b32 s0, s53, 16
	s_add_i32 s1, s0, 16
	v_add3_u32 v179, s1, v197, v195
	v_add3_u32 v178, s1, v196, v195
	s_waitcnt vmcnt(0)
	v_add_u32_e32 v128, v179, v205
	v_add_u32_e32 v180, v178, v205
	s_waitcnt lgkmcnt(0)
	s_barrier
	ds_read_b128 v[152:155], v180
	ds_read_b128 v[140:143], v128 offset:32768
	ds_read_b128 v[136:139], v128 offset:34816
	ds_read_b128 v[132:135], v128 offset:36864
	ds_read_b128 v[128:131], v128 offset:38912
	ds_read_b128 v[156:159], v180 offset:2048
	ds_read_b128 v[144:147], v180 offset:4096
	ds_read_b128 v[148:151], v180 offset:6144
	s_xor_b32 s0, s0, 0x10000
	s_cmp_gt_u32 s40, 14
	v_add_u32_e32 v176, s0, v204
	s_waitcnt lgkmcnt(6)
	v_mfma_f32_16x16x32_bf16 v[124:127], v[152:155], v[140:143], v[124:127]
	s_waitcnt lgkmcnt(5)
	v_mfma_f32_16x16x32_bf16 v[120:123], v[152:155], v[136:139], v[120:123]
	s_waitcnt lgkmcnt(4)
	v_mfma_f32_16x16x32_bf16 v[112:115], v[152:155], v[132:135], v[112:115]
	s_waitcnt lgkmcnt(3)
	v_mfma_f32_16x16x32_bf16 v[104:107], v[152:155], v[128:131], v[104:107]
	s_waitcnt lgkmcnt(2)
	v_mfma_f32_16x16x32_bf16 v[116:119], v[156:159], v[140:143], v[116:119]
	v_mfma_f32_16x16x32_bf16 v[108:111], v[156:159], v[136:139], v[108:111]
	v_mfma_f32_16x16x32_bf16 v[100:103], v[156:159], v[132:135], v[100:103]
	v_mfma_f32_16x16x32_bf16 v[96:99], v[156:159], v[128:131], v[96:99]
	s_cbranch_scc1 .LBB0_338
	v_readfirstlane_b32 s0, v176
	v_add_u32_e32 v181, 0x400, v176
	v_lshl_add_u64 v[182:183], v[174:175], 0, s[34:35]
	s_mov_b32 m0, s0
	v_readfirstlane_b32 s0, v181
	v_lshl_add_u64 v[184:185], v[172:173], 0, s[34:35]
	global_load_lds_dwordx4 v[182:183], off
	s_mov_b32 m0, s0
	s_nop 0
	global_load_lds_dwordx4 v[184:185], off
.LBB0_338:
	s_andn2_b64 vcc, exec, s[20:21]
	s_waitcnt lgkmcnt(1)
	v_mfma_f32_16x16x32_bf16 v[92:95], v[144:147], v[140:143], v[92:95]
	v_mfma_f32_16x16x32_bf16 v[88:91], v[144:147], v[136:139], v[88:91]
	v_mfma_f32_16x16x32_bf16 v[80:83], v[144:147], v[132:135], v[80:83]
	v_mfma_f32_16x16x32_bf16 v[72:75], v[144:147], v[128:131], v[72:75]
	s_waitcnt lgkmcnt(0)
	v_mfma_f32_16x16x32_bf16 v[84:87], v[148:151], v[140:143], v[84:87]
	v_mfma_f32_16x16x32_bf16 v[76:79], v[148:151], v[136:139], v[76:79]
	v_mfma_f32_16x16x32_bf16 v[68:71], v[148:151], v[132:135], v[68:71]
	v_mfma_f32_16x16x32_bf16 v[64:67], v[148:151], v[128:131], v[64:67]
	ds_read_b128 v[152:155], v180 offset:8192
	ds_read_b128 v[156:159], v180 offset:10240
	ds_read_b128 v[144:147], v180 offset:12288
	ds_read_b128 v[148:151], v180 offset:14336
	v_cndmask_b32_e64 v180, 0, 1, s[20:21]
	v_cmp_ne_u32_e64 s[0:1], 1, v180
	s_cbranch_vccnz .LBB0_340
	v_add_u32_e32 v184, 0x800, v176
	v_lshl_add_u64 v[180:181], v[170:171], 0, s[34:35]
	v_readfirstlane_b32 s20, v184
	s_mov_b32 m0, s20
	v_lshl_add_u64 v[182:183], v[168:169], 0, s[34:35]
	global_load_lds_dwordx4 v[180:181], off
	v_add_u32_e32 v180, 0xc00, v176
	s_nop 0
	v_readfirstlane_b32 s20, v180
	s_mov_b32 m0, s20
	s_nop 0
	global_load_lds_dwordx4 v[182:183], off

; #define MFMA16(a, b, c) __builtin_amdgcn_mfma_f32_16x16x32_bf16((a), (b), (c), 0, 0, 0)
; #define RAW_BARRIER() do { asm volatile("s_waitcnt lgkmcnt(0)" ::: "memory"); __builtin_amdgcn_s_barrier(); } while (0)
; template <int AMODE, bool SWAPO = true>
; DI void mainloop_dma16(f32x4 (&acc)[4][2][2][2], const TD& c, const TD& n, bool hasn, bool primed, int& s, int tid) {
;     ...
;     for (int kt = 0; kt < nk; ++kt) {
;         asm volatile("s_waitcnt vmcnt(0)" ::: "memory");
;         RAW_BARRIER();
;         const int ns = s ^ 1, nkt = kt + 1;
;         const bool doload = nkt < nk;
;         const char* sb = smem + s * C::STAGE;
; #pragma unroll
;         for (int k2 = 0; k2 < 2; ++k2) {
;             const int co = ((4 * k2 + q) ^ key) << 4;
;             bf16x8 fw[2][2];
; #pragma unroll
;             for (int ni = 0; ni < 2; ++ni)
; #pragma unroll
;                 for (int rh = 0; rh < 2; ++rh) fw[ni][rh] = *(const bf16x8*)(sb + b_off + (ni * 32 + rh * 16) * 128 + co);
; #pragma unroll
;             for (int mh = 0; mh < 2; ++mh) {
;                 bf16x8 fx[2][2];
; #pragma unroll
;                 for (int m2 = 0; m2 < 2; ++m2)
; #pragma unroll
;                     for (int ch = 0; ch < 2; ++ch) fx[m2][ch] = *(const bf16x8*)(sb + a_off + ((2 * mh + m2) * 32 + ch * 16) * 128 + co);
;                 asm volatile("" ::: "memory");
;                 if (doload) { const int p0 = (2 * k2 + mh) * 2; piece(c, ao, bo, nkt, ns, p0); piece(c, ao, bo, nkt, ns, p0 + 1); }
;                 asm volatile("" ::: "memory");
; #pragma unroll
;                 for (int m2 = 0; m2 < 2; ++m2)
; #pragma unroll
;                     for (int ni = 0; ni < 2; ++ni)
; #pragma unroll
;                         for (int rh = 0; rh < 2; ++rh)
; #pragma unroll
;                             for (int ch = 0; ch < 2; ++ch)
;                                 acc[2 * mh + m2][ni][rh][ch] = SWAPO ? MFMA16(fw[ni][rh], fx[m2][ch], acc[2 * mh + m2][ni][rh][ch]) : MFMA16(fx[m2][ch], fw[ni][rh], acc[2 * mh + m2][ni][rh][ch]);
;             }
.LBB0_581:
	s_cmp_lt_u32 s41, 15
	s_cselect_b64 s[20:21], -1, 0
	s_lshl_b32 s0, s28, 16
	s_add_i32 s1, s0, 16
	v_add3_u32 v192, s1, v181, v179
	v_add3_u32 v191, s1, v180, v179
	s_waitcnt vmcnt(0)
	v_add_u32_e32 v128, v192, v189
	v_add_u32_e32 v193, v191, v189
	s_waitcnt lgkmcnt(0)
	s_barrier
	ds_read_b128 v[152:155], v193
	ds_read_b128 v[140:143], v128 offset:32768
	ds_read_b128 v[136:139], v128 offset:34816
	ds_read_b128 v[132:135], v128 offset:36864
	ds_read_b128 v[128:131], v128 offset:38912
	ds_read_b128 v[156:159], v193 offset:2048
	ds_read_b128 v[144:147], v193 offset:4096
	ds_read_b128 v[148:151], v193 offset:6144
	s_xor_b32 s0, s0, 0x10000
	s_cmp_gt_u32 s41, 14
	v_add_u32_e32 v176, s0, v188
	s_waitcnt lgkmcnt(6)
	v_mfma_f32_16x16x32_bf16 v[124:127], v[140:143], v[152:155], v[124:127]
	s_waitcnt lgkmcnt(5)
	v_mfma_f32_16x16x32_bf16 v[120:123], v[136:139], v[152:155], v[120:123]
	s_waitcnt lgkmcnt(4)
	v_mfma_f32_16x16x32_bf16 v[116:119], v[132:135], v[152:155], v[116:119]
	s_waitcnt lgkmcnt(3)
	v_mfma_f32_16x16x32_bf16 v[112:115], v[128:131], v[152:155], v[112:115]
	s_waitcnt lgkmcnt(2)
	v_mfma_f32_16x16x32_bf16 v[108:111], v[140:143], v[156:159], v[108:111]
	v_mfma_f32_16x16x32_bf16 v[104:107], v[136:139], v[156:159], v[104:107]
	v_mfma_f32_16x16x32_bf16 v[100:103], v[132:135], v[156:159], v[100:103]
	v_mfma_f32_16x16x32_bf16 v[96:99], v[128:131], v[156:159], v[96:99]
	s_cbranch_scc1 .LBB0_583
	v_readfirstlane_b32 s0, v176
	v_lshl_add_u64 v[194:195], v[160:161], 0, s[26:27]
	s_mov_b32 m0, s0
	v_lshl_add_u64 v[196:197], v[162:163], 0, s[26:27]
	global_load_lds_dwordx4 v[194:195], off
	v_add_u32_e32 v194, 0x400, v176
	s_nop 0
	v_readfirstlane_b32 s0, v194
	s_mov_b32 m0, s0
	s_nop 0
	global_load_lds_dwordx4 v[196:197], off
.LBB0_583:
	s_andn2_b64 vcc, exec, s[20:21]
	s_waitcnt lgkmcnt(1)
	v_mfma_f32_16x16x32_bf16 v[92:95], v[140:143], v[144:147], v[92:95]
	v_mfma_f32_16x16x32_bf16 v[88:91], v[136:139], v[144:147], v[88:91]
	v_mfma_f32_16x16x32_bf16 v[84:87], v[132:135], v[144:147], v[84:87]
	v_mfma_f32_16x16x32_bf16 v[80:83], v[128:131], v[144:147], v[80:83]
	s_waitcnt lgkmcnt(0)
	v_mfma_f32_16x16x32_bf16 v[76:79], v[140:143], v[148:151], v[76:79]
	v_mfma_f32_16x16x32_bf16 v[72:75], v[136:139], v[148:151], v[72:75]
	v_mfma_f32_16x16x32_bf16 v[68:71], v[132:135], v[148:151], v[68:71]
	v_mfma_f32_16x16x32_bf16 v[64:67], v[128:131], v[148:151], v[64:67]
	ds_read_b128 v[152:155], v193 offset:8192
	ds_read_b128 v[156:159], v193 offset:10240
	ds_read_b128 v[144:147], v193 offset:12288
	ds_read_b128 v[148:151], v193 offset:14336
	v_cndmask_b32_e64 v193, 0, 1, s[20:21]
	v_cmp_ne_u32_e64 s[0:1], 1, v193
	s_cbranch_vccnz .LBB0_585
	v_add_u32_e32 v193, 0x800, v176
	v_lshl_add_u64 v[194:195], v[164:165], 0, s[26:27]
	v_readfirstlane_b32 s20, v193
	v_add_u32_e32 v193, 0xc00, v176
	s_mov_b32 m0, s20
	v_readfirstlane_b32 s20, v193
	v_lshl_add_u64 v[196:197], v[166:167], 0, s[26:27]
	global_load_lds_dwordx4 v[194:195], off
	s_mov_b32 m0, s20
	s_nop 0
	global_load_lds_dwordx4 v[196:197], off

; #define MFMA16(a, b, c) __builtin_amdgcn_mfma_f32_16x16x32_bf16((a), (b), (c), 0, 0, 0)
; #define RAW_BARRIER() do { asm volatile("s_waitcnt lgkmcnt(0)" ::: "memory"); __builtin_amdgcn_s_barrier(); } while (0)
; template <int AMODE, bool SWAPO = true>
; DI void mainloop_dma16(f32x4 (&acc)[4][2][2][2], const TD& c, const TD& n, bool hasn, bool primed, int& s, int tid) {
;     ...
;     for (int kt = 0; kt < nk; ++kt) {
;         asm volatile("s_waitcnt vmcnt(0)" ::: "memory");
;         RAW_BARRIER();
;         const int ns = s ^ 1, nkt = kt + 1;
;         const bool doload = nkt < nk;
;         const char* sb = smem + s * C::STAGE;
; #pragma unroll
;         for (int k2 = 0; k2 < 2; ++k2) {
;             const int co = ((4 * k2 + q) ^ key) << 4;
;             bf16x8 fw[2][2];
; #pragma unroll
;             for (int ni = 0; ni < 2; ++ni)
; #pragma unroll
;                 for (int rh = 0; rh < 2; ++rh) fw[ni][rh] = *(const bf16x8*)(sb + b_off + (ni * 32 + rh * 16) * 128 + co);
; #pragma unroll
;             for (int mh = 0; mh < 2; ++mh) {
;                 bf16x8 fx[2][2];
; #pragma unroll
;                 for (int m2 = 0; m2 < 2; ++m2)
; #pragma unroll
;                     for (int ch = 0; ch < 2; ++ch) fx[m2][ch] = *(const bf16x8*)(sb + a_off + ((2 * mh + m2) * 32 + ch * 16) * 128 + co);
;                 asm volatile("" ::: "memory");
;                 if (doload) { const int p0 = (2 * k2 + mh) * 2; piece(c, ao, bo, nkt, ns, p0); piece(c, ao, bo, nkt, ns, p0 + 1); }
;                 asm volatile("" ::: "memory");
; #pragma unroll
;                 for (int m2 = 0; m2 < 2; ++m2)
; #pragma unroll
;                     for (int ni = 0; ni < 2; ++ni)
; #pragma unroll
;                         for (int rh = 0; rh < 2; ++rh)
; #pragma unroll
;                             for (int ch = 0; ch < 2; ++ch)
;                                 acc[2 * mh + m2][ni][rh][ch] = SWAPO ? MFMA16(fw[ni][rh], fx[m2][ch], acc[2 * mh + m2][ni][rh][ch]) : MFMA16(fx[m2][ch], fw[ni][rh], acc[2 * mh + m2][ni][rh][ch]);
;             }
.LBB0_1029:
	s_mov_b32 s0, s34
	s_add_i32 s34, s34, 1
	s_cmp_lt_u32 s0, 31
	s_cselect_b64 s[18:19], -1, 0
	s_lshl_b32 s1, s20, 16
	s_add_i32 s38, s1, 16
	v_add3_u32 v191, s38, v179, v175
	v_add3_u32 v190, s38, v178, v175
	s_waitcnt vmcnt(0)
	v_add_u32_e32 v128, v191, v187
	v_add_u32_e32 v192, v190, v187
	s_waitcnt lgkmcnt(0)
	s_barrier
	ds_read_b128 v[152:155], v192
	ds_read_b128 v[140:143], v128 offset:32768
	ds_read_b128 v[136:139], v128 offset:34816
	ds_read_b128 v[132:135], v128 offset:36864
	ds_read_b128 v[128:131], v128 offset:38912
	ds_read_b128 v[156:159], v192 offset:2048
	ds_read_b128 v[144:147], v192 offset:4096
	ds_read_b128 v[148:151], v192 offset:6144
	s_lshr_b32 s28, s34, 1
	s_mulk_i32 s28, 0xc0
	s_and_b32 s39, s35, 64
	s_xor_b32 s1, s1, 0x10000
	s_add_i32 s28, s28, s39
	s_cmp_gt_u32 s0, 30
	v_add_u32_e32 v189, s1, v186
	s_waitcnt lgkmcnt(6)
	v_mfma_f32_16x16x32_bf16 v[124:127], v[140:143], v[152:155], v[124:127]
	s_waitcnt lgkmcnt(5)
	v_mfma_f32_16x16x32_bf16 v[120:123], v[136:139], v[152:155], v[120:123]
	s_waitcnt lgkmcnt(4)
	v_mfma_f32_16x16x32_bf16 v[116:119], v[132:135], v[152:155], v[116:119]
	s_waitcnt lgkmcnt(3)
	v_mfma_f32_16x16x32_bf16 v[112:115], v[128:131], v[152:155], v[112:115]
	s_waitcnt lgkmcnt(2)
	v_mfma_f32_16x16x32_bf16 v[108:111], v[140:143], v[156:159], v[108:111]
	v_mfma_f32_16x16x32_bf16 v[104:107], v[136:139], v[156:159], v[104:107]
	v_mfma_f32_16x16x32_bf16 v[100:103], v[132:135], v[156:159], v[100:103]
	v_mfma_f32_16x16x32_bf16 v[96:99], v[128:131], v[156:159], v[96:99]
	s_cbranch_scc1 .LBB0_1031
	s_lshl_b64 s[0:1], s[28:29], 1
	s_add_u32 s0, s2, s0
	s_addc_u32 s1, s3, s1
	v_lshl_add_u64 v[194:195], v[160:161], 1, s[0:1]
	v_lshl_add_u64 v[196:197], v[162:163], 1, s[0:1]
	v_readfirstlane_b32 s0, v189
	v_add_u32_e32 v193, 0x400, v189
	s_mov_b32 m0, s0
	v_readfirstlane_b32 s0, v193
	global_load_lds_dwordx4 v[194:195], off
	s_mov_b32 m0, s0
	s_nop 0
	global_load_lds_dwordx4 v[196:197], off
.LBB0_1031:
	s_andn2_b64 vcc, exec, s[18:19]
	s_waitcnt lgkmcnt(1)
	v_mfma_f32_16x16x32_bf16 v[92:95], v[140:143], v[144:147], v[92:95]
	v_mfma_f32_16x16x32_bf16 v[88:91], v[136:139], v[144:147], v[88:91]
	v_mfma_f32_16x16x32_bf16 v[84:87], v[132:135], v[144:147], v[84:87]
	v_mfma_f32_16x16x32_bf16 v[80:83], v[128:131], v[144:147], v[80:83]
	s_waitcnt lgkmcnt(0)
	v_mfma_f32_16x16x32_bf16 v[76:79], v[140:143], v[148:151], v[76:79]
	v_mfma_f32_16x16x32_bf16 v[72:75], v[136:139], v[148:151], v[72:75]
	v_mfma_f32_16x16x32_bf16 v[68:71], v[132:135], v[148:151], v[68:71]
	v_mfma_f32_16x16x32_bf16 v[64:67], v[128:131], v[148:151], v[64:67]
	ds_read_b128 v[152:155], v192 offset:8192
	ds_read_b128 v[156:159], v192 offset:10240
	ds_read_b128 v[144:147], v192 offset:12288
	ds_read_b128 v[148:151], v192 offset:14336
	v_cndmask_b32_e64 v192, 0, 1, s[18:19]
	v_cmp_ne_u32_e64 s[0:1], 1, v192
	s_cbranch_vccnz .LBB0_1033
	s_lshl_b64 s[18:19], s[28:29], 1
	s_add_u32 s18, s2, s18
	s_addc_u32 s19, s3, s19
	v_add_u32_e32 v196, 0x800, v189
	v_lshl_add_u64 v[192:193], v[164:165], 1, s[18:19]
	v_lshl_add_u64 v[194:195], v[176:177], 1, s[18:19]
	v_readfirstlane_b32 s18, v196
	s_mov_b32 m0, s18
	s_nop 0
	global_load_lds_dwordx4 v[192:193], off
	v_add_u32_e32 v192, 0xc00, v189
	s_nop 0
	v_readfirstlane_b32 s18, v192
	s_mov_b32 m0, s18
	s_nop 0
	global_load_lds_dwordx4 v[194:195], off

; #define MFMA16(a, b, c) __builtin_amdgcn_mfma_f32_16x16x32_bf16((a), (b), (c), 0, 0, 0)
; #define RAW_BARRIER() do { asm volatile("s_waitcnt lgkmcnt(0)" ::: "memory"); __builtin_amdgcn_s_barrier(); } while (0)
; template <int AMODE, bool SWAPO = true>
; DI void mainloop_dma16(f32x4 (&acc)[4][2][2][2], const TD& c, const TD& n, bool hasn, bool primed, int& s, int tid) {
;     ...
;     for (int kt = 0; kt < nk; ++kt) {
;         asm volatile("s_waitcnt vmcnt(0)" ::: "memory");
;         RAW_BARRIER();
;         const int ns = s ^ 1, nkt = kt + 1;
;         const bool doload = nkt < nk;
;         const char* sb = smem + s * C::STAGE;
; #pragma unroll
;         for (int k2 = 0; k2 < 2; ++k2) {
;             const int co = ((4 * k2 + q) ^ key) << 4;
;             bf16x8 fw[2][2];
; #pragma unroll
;             for (int ni = 0; ni < 2; ++ni)
; #pragma unroll
;                 for (int rh = 0; rh < 2; ++rh) fw[ni][rh] = *(const bf16x8*)(sb + b_off + (ni * 32 + rh * 16) * 128 + co);
; #pragma unroll
;             for (int mh = 0; mh < 2; ++mh) {
;                 bf16x8 fx[2][2];
; #pragma unroll
;                 for (int m2 = 0; m2 < 2; ++m2)
; #pragma unroll
;                     for (int ch = 0; ch < 2; ++ch) fx[m2][ch] = *(const bf16x8*)(sb + a_off + ((2 * mh + m2) * 32 + ch * 16) * 128 + co);
;                 asm volatile("" ::: "memory");
;                 if (doload) { const int p0 = (2 * k2 + mh) * 2; piece(c, ao, bo, nkt, ns, p0); piece(c, ao, bo, nkt, ns, p0 + 1); }
;                 asm volatile("" ::: "memory");
; #pragma unroll
;                 for (int m2 = 0; m2 < 2; ++m2)
; #pragma unroll
;                     for (int ni = 0; ni < 2; ++ni)
; #pragma unroll
;                         for (int rh = 0; rh < 2; ++rh)
; #pragma unroll
;                             for (int ch = 0; ch < 2; ++ch)
;                                 acc[2 * mh + m2][ni][rh][ch] = SWAPO ? MFMA16(fw[ni][rh], fx[m2][ch], acc[2 * mh + m2][ni][rh][ch]) : MFMA16(fx[m2][ch], fw[ni][rh], acc[2 * mh + m2][ni][rh][ch]);
;             }
.LBB0_1196:
	s_cmp_lt_u32 s27, 15
	s_cselect_b64 s[18:19], -1, 0
	s_lshl_b32 s0, s28, 16
	s_add_i32 s1, s0, 16
	v_add3_u32 v192, s1, v181, v179
	v_add3_u32 v191, s1, v180, v179
	s_waitcnt vmcnt(0)
	v_add_u32_e32 v128, v192, v189
	v_add_u32_e32 v193, v191, v189
	s_waitcnt lgkmcnt(0)
	s_barrier
	ds_read_b128 v[152:155], v193
	ds_read_b128 v[140:143], v128 offset:32768
	ds_read_b128 v[136:139], v128 offset:34816
	ds_read_b128 v[132:135], v128 offset:36864
	ds_read_b128 v[128:131], v128 offset:38912
	ds_read_b128 v[156:159], v193 offset:2048
	ds_read_b128 v[144:147], v193 offset:4096
	ds_read_b128 v[148:151], v193 offset:6144
	s_xor_b32 s0, s0, 0x10000
	s_cmp_gt_u32 s27, 14
	v_add_u32_e32 v176, s0, v188
	s_waitcnt lgkmcnt(6)
	v_mfma_f32_16x16x32_bf16 v[120:123], v[152:155], v[140:143], v[120:123]
	s_waitcnt lgkmcnt(5)
	v_mfma_f32_16x16x32_bf16 v[56:59], v[152:155], v[136:139], v[56:59]
	s_waitcnt lgkmcnt(4)
	v_mfma_f32_16x16x32_bf16 v[124:127], v[152:155], v[132:135], v[124:127]
	s_waitcnt lgkmcnt(3)
	v_mfma_f32_16x16x32_bf16 v[60:63], v[152:155], v[128:131], v[60:63]
	s_waitcnt lgkmcnt(2)
	v_mfma_f32_16x16x32_bf16 v[112:115], v[156:159], v[140:143], v[112:115]
	v_mfma_f32_16x16x32_bf16 v[48:51], v[156:159], v[136:139], v[48:51]
	v_mfma_f32_16x16x32_bf16 v[116:119], v[156:159], v[132:135], v[116:119]
	v_mfma_f32_16x16x32_bf16 v[52:55], v[156:159], v[128:131], v[52:55]
	s_cbranch_scc1 .LBB0_1198
	v_readfirstlane_b32 s0, v176
	v_lshl_add_u64 v[194:195], v[160:161], 0, s[4:5]
	s_mov_b32 m0, s0
	v_lshl_add_u64 v[196:197], v[162:163], 0, s[4:5]
	global_load_lds_dwordx4 v[194:195], off
	v_add_u32_e32 v194, 0x400, v176
	s_nop 0
	v_readfirstlane_b32 s0, v194
	s_mov_b32 m0, s0
	s_nop 0
	global_load_lds_dwordx4 v[196:197], off
.LBB0_1198:
	s_andn2_b64 vcc, exec, s[18:19]
	s_waitcnt lgkmcnt(1)
	v_mfma_f32_16x16x32_bf16 v[104:107], v[144:147], v[140:143], v[104:107]
	v_mfma_f32_16x16x32_bf16 v[40:43], v[144:147], v[136:139], v[40:43]
	v_mfma_f32_16x16x32_bf16 v[108:111], v[144:147], v[132:135], v[108:111]
	v_mfma_f32_16x16x32_bf16 v[44:47], v[144:147], v[128:131], v[44:47]
	s_waitcnt lgkmcnt(0)
	v_mfma_f32_16x16x32_bf16 v[96:99], v[148:151], v[140:143], v[96:99]
	v_mfma_f32_16x16x32_bf16 v[32:35], v[148:151], v[136:139], v[32:35]
	v_mfma_f32_16x16x32_bf16 v[100:103], v[148:151], v[132:135], v[100:103]
	v_mfma_f32_16x16x32_bf16 v[36:39], v[148:151], v[128:131], v[36:39]
	ds_read_b128 v[152:155], v193 offset:8192
	ds_read_b128 v[156:159], v193 offset:10240
	ds_read_b128 v[144:147], v193 offset:12288
	ds_read_b128 v[148:151], v193 offset:14336
	v_cndmask_b32_e64 v193, 0, 1, s[18:19]
	v_cmp_ne_u32_e64 s[0:1], 1, v193
	s_cbranch_vccnz .LBB0_1200
	v_add_u32_e32 v193, 0x800, v176
	v_lshl_add_u64 v[194:195], v[164:165], 0, s[4:5]
	v_readfirstlane_b32 s18, v193
	v_add_u32_e32 v193, 0xc00, v176
	s_mov_b32 m0, s18
	v_readfirstlane_b32 s18, v193
	v_lshl_add_u64 v[196:197], v[166:167], 0, s[4:5]
	global_load_lds_dwordx4 v[194:195], off
	s_mov_b32 m0, s18
	s_nop 0
	global_load_lds_dwordx4 v[196:197], off
